# v49 + tile-to-block permutation in the three 160x128-tile phases (co-resident block pair shares the A tile)
# baseline (speedup 1.0000x reference)
.LBB0_83:
	s_lshl_b32 s8, s34, 3
	s_mul_i32 s9, s8, s2
	s_cmpk_gt_i32 s9, 0x33f
	s_mov_b32 s35, 2
	s_mov_b64 s[40:41], 0x10000
	s_cbranch_scc1 .LBB0_92
	s_or_b32 s8, s8, s14
	s_mul_i32 s8, s8, s2
	s_and_b32 s9, s15, 31
	s_lshr_b32 s10, s9, 2
	s_and_b32 s9, s9, 3
	s_lshl_b32 s9, s9, 1
	s_lshl_b32 s10, s10, 3
	s_or_b32 s9, s9, s10
	s_lshr_b32 s10, s10, 3
	s_and_b32 s10, s10, 1
	s_or_b32 s9, s9, s10
	s_lshr_b32 s10, s15, 5
	s_and_b32 s10, s10, 1
	s_xor_b32 s9, s9, s10
	s_add_i32 s8, s8, s9
	s_cmpk_gt_i32 s8, 0x33f
	s_mov_b32 s35, 4
	s_cbranch_scc1 .LBB0_92
	s_mul_hi_i32 s9, s8, 0x4ec4ec4f
	s_lshr_b32 s10, s9, 31
	s_ashr_i32 s9, s9, 8
	s_add_i32 s9, s9, s10
	s_lshl_b32 s10, s9, 3
	s_mulk_i32 s9, 0x340
	s_sub_i32 s8, s8, s9
	s_ashr_i32 s36, s8, 3
	s_and_b32 s9, s8, 7
	s_mul_i32 s12, s36, 0x1f4000
	s_or_b32 s10, s10, s9
	s_ashr_i32 s13, s12, 31
	s_add_u32 s38, s0, s12
	s_addc_u32 s39, s1, s13
	s_ashr_i32 s11, s10, 31
	s_lshl_b64 s[8:9], s[10:11], 18
	v_lshl_add_u64 v[102:103], s[38:39], 0, v[82:83]
	v_lshlrev_b32_e32 v96, 1, v80
	v_readfirstlane_b32 s11, v81
	v_add_u32_e32 v133, 0x1000, v81
	v_lshl_add_u64 v[104:105], v[102:103], 0, v[96:97]
	s_mov_b32 m0, s11
	s_mov_b64 s[38:39], 0x64000
	v_readfirstlane_b32 s11, v133
	v_add_u32_e32 v132, 0x2000, v81
	global_load_lds_dwordx4 v[104:105], off
	v_lshl_add_u64 v[0:1], v[104:105], 0, s[38:39]
	s_mov_b32 m0, s11
	s_mov_b64 s[38:39], 0xc8000
	v_readfirstlane_b32 s11, v132
	v_add_u32_e32 v131, 0x3000, v81
	global_load_lds_dwordx4 v[0:1], off
	v_lshl_add_u64 v[0:1], v[104:105], 0, s[38:39]
	s_mov_b32 m0, s11
	s_mov_b64 s[38:39], 0x12c000
	v_readfirstlane_b32 s11, v131
	v_add_u32_e32 v130, 0x4000, v81
	global_load_lds_dwordx4 v[0:1], off
	v_lshl_add_u64 v[0:1], v[104:105], 0, s[38:39]
	s_mov_b32 m0, s11
	s_mov_b64 s[38:39], 0x190000
	v_readfirstlane_b32 s11, v130
	v_add_u32_e32 v129, 0x5000, v81
	global_load_lds_dwordx4 v[0:1], off
	v_lshl_add_u64 v[0:1], v[104:105], 0, s[38:39]
	s_mov_b32 m0, s11
	v_readfirstlane_b32 s11, v129
	v_add_u32_e32 v128, 0x6000, v81
	global_load_lds_dwordx4 v[0:1], off
	v_lshl_add_u64 v[0:1], v[84:85], 0, s[8:9]
	s_mov_b32 m0, s11
	v_readfirstlane_b32 s11, v128
	v_add_u32_e32 v127, 0x7000, v81
	global_load_lds_dwordx4 v[0:1], off
	v_lshl_add_u64 v[2:3], v[0:1], 0, s[40:41]
	s_mov_b32 m0, s11
	s_mov_b64 s[38:39], 0x20000
	v_readfirstlane_b32 s11, v127
	v_add_u32_e32 v126, 0x8000, v81
	global_load_lds_dwordx4 v[2:3], off
	v_lshl_add_u64 v[2:3], v[0:1], 0, s[38:39]
	s_mov_b32 m0, s11
	s_mov_b64 s[38:39], 0x30000
	v_readfirstlane_b32 s11, v126
	global_load_lds_dwordx4 v[2:3], off
	v_lshl_add_u64 v[0:1], v[0:1], 0, s[38:39]
	s_mov_b32 m0, s11
	v_lshl_add_u64 v[94:95], v[90:91], 0, s[12:13]
	global_load_lds_dwordx4 v[0:1], off
	s_waitcnt vmcnt(0)
	v_mov_b32_e32 v0, 0
	v_lshl_add_u64 v[100:101], v[92:93], 0, s[8:9]
	s_mov_b32 s11, 0
	s_mov_b64 s[12:13], 0
	v_mov_b32_e32 v1, v0
	v_mov_b32_e32 v2, v0
	v_mov_b32_e32 v3, v0
	v_mov_b32_e32 v4, v0
	v_mov_b32_e32 v5, v0
	v_mov_b32_e32 v6, v0
	v_mov_b32_e32 v7, v0
	v_mov_b32_e32 v8, v0
	v_mov_b32_e32 v9, v0
	v_mov_b32_e32 v10, v0
	v_mov_b32_e32 v11, v0
	v_mov_b32_e32 v12, v0
	v_mov_b32_e32 v13, v0
	v_mov_b32_e32 v14, v0
	v_mov_b32_e32 v15, v0
	v_mov_b32_e32 v16, v0
	v_mov_b32_e32 v17, v0
	v_mov_b32_e32 v18, v0
	v_mov_b32_e32 v19, v0
	v_mov_b32_e32 v20, v0
	v_mov_b32_e32 v21, v0
	v_mov_b32_e32 v22, v0
	v_mov_b32_e32 v23, v0
	v_mov_b32_e32 v24, v0
	v_mov_b32_e32 v25, v0
	v_mov_b32_e32 v26, v0
	v_mov_b32_e32 v27, v0
	v_mov_b32_e32 v28, v0
	v_mov_b32_e32 v29, v0
	v_mov_b32_e32 v30, v0
	v_mov_b32_e32 v31, v0
	v_mov_b32_e32 v32, v0
	v_mov_b32_e32 v33, v0
	v_mov_b32_e32 v34, v0
	v_mov_b32_e32 v35, v0
	v_mov_b32_e32 v36, v0
	v_mov_b32_e32 v37, v0
	v_mov_b32_e32 v38, v0
	v_mov_b32_e32 v39, v0
	v_mov_b32_e32 v40, v0
	v_mov_b32_e32 v41, v0
	v_mov_b32_e32 v42, v0
	v_mov_b32_e32 v43, v0
	v_mov_b32_e32 v44, v0
	v_mov_b32_e32 v45, v0
	v_mov_b32_e32 v46, v0
	v_mov_b32_e32 v47, v0
	v_mov_b32_e32 v48, v0
	v_mov_b32_e32 v49, v0
	v_mov_b32_e32 v50, v0
	v_mov_b32_e32 v51, v0
	v_mov_b32_e32 v52, v0
	v_mov_b32_e32 v53, v0
	v_mov_b32_e32 v54, v0
	v_mov_b32_e32 v55, v0
	v_mov_b32_e32 v56, v0
	v_mov_b32_e32 v57, v0
	v_mov_b32_e32 v58, v0
	v_mov_b32_e32 v59, v0
	v_mov_b32_e32 v60, v0
	v_mov_b32_e32 v61, v0
	v_mov_b32_e32 v62, v0
	v_mov_b32_e32 v63, v0
	v_mov_b32_e32 v64, v0
	v_mov_b32_e32 v65, v0
	v_mov_b32_e32 v66, v0
	v_mov_b32_e32 v67, v0
	v_mov_b32_e32 v68, v0
	v_mov_b32_e32 v69, v0
	v_mov_b32_e32 v70, v0
	v_mov_b32_e32 v71, v0
	v_mov_b32_e32 v72, v0
	v_mov_b32_e32 v73, v0
	v_mov_b32_e32 v74, v0
	v_mov_b32_e32 v75, v0
	v_mov_b32_e32 v76, v0
	v_mov_b32_e32 v77, v0
	v_mov_b32_e32 v78, v0
	v_mov_b32_e32 v79, v0
	s_waitcnt vmcnt(0) lgkmcnt(0)
	s_barrier

.LBB0_134:
	s_lshl_b32 s10, s36, 3
	s_mul_i32 s11, s10, s2
	s_cmpk_gt_i32 s11, 0x33f
	s_mov_b32 s37, 2
	s_mov_b64 s[44:45], 0x10000
	s_cbranch_scc1 .LBB0_139
	s_or_b32 s10, s10, s14
	s_mul_i32 s10, s10, s2
	s_and_b32 s11, s15, 31
	s_lshr_b32 s12, s11, 2
	s_and_b32 s11, s11, 3
	s_lshl_b32 s11, s11, 1
	s_lshl_b32 s12, s12, 3
	s_or_b32 s11, s11, s12
	s_lshr_b32 s12, s12, 3
	s_and_b32 s12, s12, 1
	s_or_b32 s11, s11, s12
	s_lshr_b32 s12, s15, 5
	s_and_b32 s12, s12, 1
	s_xor_b32 s11, s11, s12
	s_add_i32 s10, s10, s11
	s_cmpk_gt_i32 s10, 0x33f
	s_mov_b32 s37, 4
	s_cbranch_scc1 .LBB0_139
	s_mul_hi_i32 s11, s10, 0x4ec4ec4f
	s_lshr_b32 s12, s11, 31
	s_ashr_i32 s11, s11, 8
	s_add_i32 s11, s11, s12
	s_lshl_b32 s12, s11, 3
	s_mulk_i32 s11, 0x340
	s_sub_i32 s10, s10, s11
	s_and_b32 s11, s10, 7
	s_ashr_i32 s38, s10, 3
	s_or_b32 s10, s12, s11
	s_mul_i32 s12, s38, 0x50000
	s_ashr_i32 s13, s12, 31
	v_readfirstlane_b32 s11, v177
	v_add_u32_e32 v4, 0x1000, v177
	v_lshl_add_u64 v[0:1], v[80:81], 0, s[12:13]
	s_mov_b32 m0, s11
	v_readfirstlane_b32 s11, v4
	v_add_u32_e32 v4, 0x2000, v177
	global_load_lds_dwordx4 v[0:1], off
	v_lshl_add_u64 v[2:3], v[0:1], 0, s[44:45]
	s_mov_b32 m0, s11
	s_mov_b64 s[46:47], 0x20000
	v_readfirstlane_b32 s11, v4
	v_add_u32_e32 v4, 0x3000, v177
	global_load_lds_dwordx4 v[2:3], off
	v_lshl_add_u64 v[2:3], v[0:1], 0, s[46:47]
	s_mov_b32 m0, s11
	s_mov_b64 s[48:49], 0x30000
	v_readfirstlane_b32 s11, v4
	global_load_lds_dwordx4 v[2:3], off
	v_lshl_add_u64 v[2:3], v[0:1], 0, s[48:49]
	s_mov_b32 m0, s11
	s_add_i32 s10, s10, 16
	global_load_lds_dwordx4 v[2:3], off
	v_add_u32_e32 v2, 0x4000, v177
	s_mov_b64 s[40:41], 0x40000
	v_readfirstlane_b32 s11, v2
	s_mov_b32 m0, s11
	s_ashr_i32 s11, s10, 31
	v_add_u32_e32 v2, 0x5000, v177
	v_lshl_add_u64 v[0:1], v[0:1], 0, s[40:41]
	s_lshl_b64 s[40:41], s[10:11], 18
	v_readfirstlane_b32 s11, v2
	v_add_u32_e32 v4, 0x6000, v177
	global_load_lds_dwordx4 v[0:1], off
	v_lshl_add_u64 v[0:1], v[82:83], 0, s[40:41]
	s_mov_b32 m0, s11
	v_readfirstlane_b32 s11, v4
	v_add_u32_e32 v4, 0x7000, v177
	global_load_lds_dwordx4 v[0:1], off
	v_lshl_add_u64 v[2:3], v[0:1], 0, s[44:45]
	s_mov_b32 m0, s11
	v_readfirstlane_b32 s11, v4
	global_load_lds_dwordx4 v[2:3], off
	v_lshl_add_u64 v[2:3], v[0:1], 0, s[46:47]
	s_mov_b32 m0, s11
	v_lshl_add_u64 v[0:1], v[0:1], 0, s[48:49]
	global_load_lds_dwordx4 v[2:3], off
	v_add_u32_e32 v2, 0x8000, v177
	v_lshl_add_u64 v[86:87], v[84:85], 0, s[12:13]
	v_readfirstlane_b32 s11, v2
	s_mov_b32 m0, s11
	v_lshl_add_u64 v[88:89], v[84:85], 0, s[40:41]
	global_load_lds_dwordx4 v[0:1], off
	s_waitcnt vmcnt(0)
	v_mov_b32_e32 v0, 0
	s_waitcnt vmcnt(0) lgkmcnt(0)
	s_barrier
	s_mov_b32 s11, 0
	s_mov_b64 s[12:13], 0
	v_mov_b32_e32 v1, v0
	v_mov_b32_e32 v2, v0
	v_mov_b32_e32 v3, v0
	v_mov_b32_e32 v4, v0
	v_mov_b32_e32 v5, v0
	v_mov_b32_e32 v6, v0
	v_mov_b32_e32 v7, v0
	v_mov_b32_e32 v8, v0
	v_mov_b32_e32 v9, v0
	v_mov_b32_e32 v10, v0
	v_mov_b32_e32 v11, v0
	v_mov_b32_e32 v12, v0
	v_mov_b32_e32 v13, v0
	v_mov_b32_e32 v14, v0
	v_mov_b32_e32 v15, v0
	v_mov_b32_e32 v16, v0
	v_mov_b32_e32 v17, v0
	v_mov_b32_e32 v18, v0
	v_mov_b32_e32 v19, v0
	v_mov_b32_e32 v20, v0
	v_mov_b32_e32 v21, v0
	v_mov_b32_e32 v22, v0
	v_mov_b32_e32 v23, v0
	v_mov_b32_e32 v24, v0
	v_mov_b32_e32 v25, v0
	v_mov_b32_e32 v26, v0
	v_mov_b32_e32 v27, v0
	v_mov_b32_e32 v28, v0
	v_mov_b32_e32 v29, v0
	v_mov_b32_e32 v30, v0
	v_mov_b32_e32 v31, v0
	v_mov_b32_e32 v32, v0
	v_mov_b32_e32 v33, v0
	v_mov_b32_e32 v34, v0
	v_mov_b32_e32 v35, v0
	v_mov_b32_e32 v36, v0
	v_mov_b32_e32 v37, v0
	v_mov_b32_e32 v38, v0
	v_mov_b32_e32 v39, v0
	v_mov_b32_e32 v40, v0
	v_mov_b32_e32 v41, v0
	v_mov_b32_e32 v42, v0
	v_mov_b32_e32 v43, v0
	v_mov_b32_e32 v44, v0
	v_mov_b32_e32 v45, v0
	v_mov_b32_e32 v46, v0
	v_mov_b32_e32 v47, v0
	v_mov_b32_e32 v48, v0
	v_mov_b32_e32 v49, v0
	v_mov_b32_e32 v50, v0
	v_mov_b32_e32 v51, v0
	v_mov_b32_e32 v52, v0
	v_mov_b32_e32 v53, v0
	v_mov_b32_e32 v54, v0
	v_mov_b32_e32 v55, v0
	v_mov_b32_e32 v56, v0
	v_mov_b32_e32 v57, v0
	v_mov_b32_e32 v58, v0
	v_mov_b32_e32 v59, v0
	v_mov_b32_e32 v60, v0
	v_mov_b32_e32 v61, v0
	v_mov_b32_e32 v62, v0
	v_mov_b32_e32 v63, v0
	v_mov_b32_e32 v64, v0
	v_mov_b32_e32 v65, v0
	v_mov_b32_e32 v66, v0
	v_mov_b32_e32 v67, v0
	v_mov_b32_e32 v68, v0
	v_mov_b32_e32 v69, v0
	v_mov_b32_e32 v70, v0
	v_mov_b32_e32 v71, v0
	v_mov_b32_e32 v72, v0
	v_mov_b32_e32 v73, v0
	v_mov_b32_e32 v74, v0
	v_mov_b32_e32 v75, v0
	v_mov_b32_e32 v76, v0
	v_mov_b32_e32 v77, v0
	v_mov_b32_e32 v78, v0
	v_mov_b32_e32 v79, v0
	s_mov_b64 s[44:45], 0x4101080
	s_mov_b64 s[46:47], 0x4111080
	s_mov_b64 s[48:49], 0x4121080
	s_mov_b64 s[52:53], 0x4131080
	s_mov_b64 s[54:55], 0x13931080
	s_mov_b64 s[56:57], 0x13941080
	s_mov_b64 s[58:59], 0x13951080
	s_mov_b64 s[60:61], 0x13961080

.LBB0_579:
	s_lshl_b32 s4, s12, 3
	s_mul_i32 s5, s4, s2
	s_cmpk_gt_i32 s5, 0x33f
	s_mov_b32 s8, 2
	s_cbranch_scc1 .LBB0_584
	s_or_b32 s4, s4, s10
	s_mul_i32 s4, s4, s2
	s_and_b32 s5, s11, 31
	s_lshr_b32 s6, s5, 2
	s_and_b32 s5, s5, 3
	s_lshl_b32 s5, s5, 1
	s_lshl_b32 s6, s6, 3
	s_or_b32 s5, s5, s6
	s_lshr_b32 s6, s6, 3
	s_and_b32 s6, s6, 1
	s_or_b32 s5, s5, s6
	s_lshr_b32 s6, s11, 5
	s_and_b32 s6, s6, 1
	s_xor_b32 s5, s5, s6
	s_add_i32 s4, s4, s5
	s_cmpk_gt_i32 s4, 0x33f
	s_mov_b32 s8, 4
	s_cbranch_scc1 .LBB0_584
	s_mul_hi_i32 s5, s4, 0x4ec4ec4f
	s_lshr_b32 s6, s5, 31
	s_ashr_i32 s5, s5, 8
	s_add_i32 s5, s5, s6
	s_mul_i32 s6, s5, 0x340
	s_sub_i32 s4, s4, s6
	s_lshr_b32 s6, s4, 3
	s_lshl_b32 s5, s5, 3
	s_and_b32 s4, s4, 7
	s_or_b32 s4, s5, s4
	s_mulk_i32 s6, 0xa0
	s_ashr_i32 s7, s6, 31
	s_ashr_i32 s5, s4, 31
	s_lshl_b64 s[8:9], s[6:7], 11
	s_lshl_b64 s[14:15], s[4:5], 18
	v_readfirstlane_b32 s5, v92
	v_add_u32_e32 v4, 0x1000, v92
	v_lshl_add_u64 v[0:1], v[80:81], 0, s[8:9]
	s_mov_b32 m0, s5
	s_mov_b64 s[34:35], 0x10000
	v_readfirstlane_b32 s5, v4
	v_add_u32_e32 v4, 0x2000, v92
	global_load_lds_dwordx4 v[0:1], off
	v_lshl_add_u64 v[2:3], v[0:1], 0, s[34:35]
	s_mov_b32 m0, s5
	s_mov_b64 s[36:37], 0x20000
	v_readfirstlane_b32 s5, v4
	v_add_u32_e32 v4, 0x3000, v92
	global_load_lds_dwordx4 v[2:3], off
	v_lshl_add_u64 v[2:3], v[0:1], 0, s[36:37]
	s_mov_b32 m0, s5
	s_mov_b64 s[38:39], 0x30000
	v_readfirstlane_b32 s5, v4
	global_load_lds_dwordx4 v[2:3], off
	v_lshl_add_u64 v[2:3], v[0:1], 0, s[38:39]
	s_mov_b32 m0, s5
	s_mov_b64 s[40:41], 0x40000
	global_load_lds_dwordx4 v[2:3], off
	v_add_u32_e32 v2, 0x4000, v92
	v_lshl_add_u64 v[0:1], v[0:1], 0, s[40:41]
	v_readfirstlane_b32 s5, v2
	v_add_u32_e32 v2, 0x5000, v92
	s_mov_b32 m0, s5
	v_readfirstlane_b32 s5, v2
	v_add_u32_e32 v4, 0x6000, v92
	global_load_lds_dwordx4 v[0:1], off
	v_lshl_add_u64 v[0:1], v[82:83], 0, s[14:15]
	s_mov_b32 m0, s5
	v_readfirstlane_b32 s5, v4
	v_add_u32_e32 v4, 0x7000, v92
	global_load_lds_dwordx4 v[0:1], off
	v_lshl_add_u64 v[2:3], v[0:1], 0, s[34:35]
	s_mov_b32 m0, s5
	v_readfirstlane_b32 s5, v4
	global_load_lds_dwordx4 v[2:3], off
	v_lshl_add_u64 v[2:3], v[0:1], 0, s[36:37]
	s_mov_b32 m0, s5
	v_lshl_add_u64 v[0:1], v[0:1], 0, s[38:39]
	global_load_lds_dwordx4 v[2:3], off
	v_add_u32_e32 v2, 0x8000, v92
	v_lshl_add_u64 v[88:89], v[84:85], 0, s[8:9]
	v_readfirstlane_b32 s5, v2
	s_mov_b32 m0, s5
	v_lshl_add_u64 v[90:91], v[86:87], 0, s[14:15]
	global_load_lds_dwordx4 v[0:1], off
	s_waitcnt vmcnt(0)
	v_mov_b32_e32 v0, 0
	s_mov_b32 s5, 0
	s_mov_b64 s[8:9], 0
	v_mov_b32_e32 v1, v0
	v_mov_b32_e32 v2, v0
	v_mov_b32_e32 v3, v0
	v_mov_b32_e32 v4, v0
	v_mov_b32_e32 v5, v0
	v_mov_b32_e32 v6, v0
	v_mov_b32_e32 v7, v0
	v_mov_b32_e32 v8, v0
	v_mov_b32_e32 v9, v0
	v_mov_b32_e32 v10, v0
	v_mov_b32_e32 v11, v0
	v_mov_b32_e32 v12, v0
	v_mov_b32_e32 v13, v0
	v_mov_b32_e32 v14, v0
	v_mov_b32_e32 v15, v0
	v_mov_b32_e32 v16, v0
	v_mov_b32_e32 v17, v0
	v_mov_b32_e32 v18, v0
	v_mov_b32_e32 v19, v0
	v_mov_b32_e32 v20, v0
	v_mov_b32_e32 v21, v0
	v_mov_b32_e32 v22, v0
	v_mov_b32_e32 v23, v0
	v_mov_b32_e32 v24, v0
	v_mov_b32_e32 v25, v0
	v_mov_b32_e32 v26, v0
	v_mov_b32_e32 v27, v0
	v_mov_b32_e32 v28, v0
	v_mov_b32_e32 v29, v0
	v_mov_b32_e32 v30, v0
	v_mov_b32_e32 v31, v0
	v_mov_b32_e32 v32, v0
	v_mov_b32_e32 v33, v0
	v_mov_b32_e32 v34, v0
	v_mov_b32_e32 v35, v0
	v_mov_b32_e32 v36, v0
	v_mov_b32_e32 v37, v0
	v_mov_b32_e32 v38, v0
	v_mov_b32_e32 v39, v0
	v_mov_b32_e32 v40, v0
	v_mov_b32_e32 v41, v0
	v_mov_b32_e32 v42, v0
	v_mov_b32_e32 v43, v0
	v_mov_b32_e32 v44, v0
	v_mov_b32_e32 v45, v0
	v_mov_b32_e32 v46, v0
	v_mov_b32_e32 v47, v0
	v_mov_b32_e32 v48, v0
	v_mov_b32_e32 v49, v0
	v_mov_b32_e32 v50, v0
	v_mov_b32_e32 v51, v0
	v_mov_b32_e32 v52, v0
	v_mov_b32_e32 v53, v0
	v_mov_b32_e32 v54, v0
	v_mov_b32_e32 v55, v0
	v_mov_b32_e32 v56, v0
	v_mov_b32_e32 v57, v0
	v_mov_b32_e32 v58, v0
	v_mov_b32_e32 v59, v0
	v_mov_b32_e32 v60, v0
	v_mov_b32_e32 v61, v0
	v_mov_b32_e32 v62, v0
	v_mov_b32_e32 v63, v0
	v_mov_b32_e32 v64, v0
	v_mov_b32_e32 v65, v0
	v_mov_b32_e32 v66, v0
	v_mov_b32_e32 v67, v0
	v_mov_b32_e32 v68, v0
	v_mov_b32_e32 v69, v0
	v_mov_b32_e32 v70, v0
	v_mov_b32_e32 v71, v0
	v_mov_b32_e32 v72, v0
	v_mov_b32_e32 v73, v0
	v_mov_b32_e32 v74, v0
	v_mov_b32_e32 v75, v0
	v_mov_b32_e32 v76, v0
	v_mov_b32_e32 v77, v0
	v_mov_b32_e32 v78, v0
	v_mov_b32_e32 v79, v0
	s_waitcnt vmcnt(0) lgkmcnt(0)
	s_barrier
